# ssd_sample dt: the per-head bias scalar loaded once instead of once per token (3 exposed round trips per unit removed)
# baseline (speedup 1.0000x reference)
.LBB0_721:
	s_or_b64 exec, exec, s[2:3]
	s_add_i32 s2, s95, s12
	s_ashr_i32 s3, s2, 31
	s_lshl_b64 s[6:7], s[2:3], 11
	s_add_u32 s6, s29, s6
	s_addc_u32 s7, s67, s7
	v_lshlrev_b32_e32 v54, 5, v159
	v_mov_b32_e32 v55, v3
	v_lshl_add_u64 v[56:57], s[6:7], 0, v[54:55]
	s_mov_b64 s[6:7], 0x680000
	v_lshl_add_u64 v[58:59], v[56:57], 0, s[6:7]
	v_add_co_u32_e32 v56, vcc, 0x680000, v56
	s_add_i32 s2, s2, s10
	s_nop 0
	v_addc_co_u32_e32 v57, vcc, 0, v57, vcc
	global_load_dwordx4 v[60:63], v[56:57], off
	global_load_dwordx4 v[74:77], v[58:59], off offset:16
	v_and_b32_e32 v56, 64, v193
	v_add_u32_e32 v56, 64, v56
	v_xor_b32_e32 v57, 1, v193
	v_cmp_lt_i32_e32 vcc, v57, v56
	s_ashr_i32 s3, s2, 31
	v_readlane_b32 s6, v255, 9
	v_cndmask_b32_e32 v57, v193, v57, vcc
	v_lshlrev_b32_e32 v161, 2, v57
	v_xor_b32_e32 v57, 2, v193
	v_cmp_lt_i32_e32 vcc, v57, v56
	s_lshl_b64 s[2:3], s[2:3], 2
	v_readlane_b32 s7, v255, 10
	v_cndmask_b32_e32 v57, v193, v57, vcc
	v_lshlrev_b32_e32 v163, 2, v57
	v_xor_b32_e32 v57, 4, v193
	v_cmp_lt_i32_e32 vcc, v57, v56
	s_add_u32 s2, s82, s2
	v_lshl_add_u64 v[54:55], s[6:7], 0, v[54:55]
	v_cndmask_b32_e32 v57, v193, v57, vcc
	v_lshlrev_b32_e32 v165, 2, v57
	v_xor_b32_e32 v57, 8, v193
	v_cmp_lt_i32_e32 vcc, v57, v56
	s_addc_u32 s3, s83, s3
	s_lshl_b32 s8, s97, 11
	v_cndmask_b32_e32 v57, v193, v57, vcc
	v_lshlrev_b32_e32 v167, 2, v57
	v_xor_b32_e32 v57, 16, v193
	v_cmp_lt_i32_e32 vcc, v57, v56
	s_lshl_b32 s6, s97, 6
	v_mov_b32_e32 v88, s6
	v_cndmask_b32_e32 v57, v193, v57, vcc
	v_lshlrev_b32_e32 v169, 2, v57
	v_xor_b32_e32 v57, 32, v193
	v_cmp_lt_i32_e32 vcc, v57, v56
	v_readlane_b32 s6, v255, 11
	v_readlane_b32 s7, v255, 12
	v_cndmask_b32_e32 v56, v193, v57, vcc
	v_lshlrev_b32_e32 v184, 2, v56
	v_lshl_add_u64 v[56:57], v[54:55], 0, s[8:9]
	global_load_dwordx4 v[78:81], v[56:57], off offset:16
	global_load_dwordx4 v[82:85], v[56:57], off
	v_lshlrev_b32_e32 v66, 4, v64
	s_waitcnt vmcnt(3)
	v_and_b32_e32 v69, 0xffff0000, v60
	v_lshlrev_b32_e32 v67, 16, v60
	s_waitcnt vmcnt(2)
	v_and_b32_e32 v71, 0xffff0000, v74
	v_lshlrev_b32_e32 v68, 16, v74
	v_and_b32_e32 v73, 0xffff0000, v61
	v_lshlrev_b32_e32 v70, 16, v61
	v_and_b32_e32 v74, 0xffff0000, v75
	v_lshlrev_b32_e32 v72, 16, v75
	v_and_b32_e32 v59, 0xffff0000, v62
	s_waitcnt vmcnt(1)
	v_and_b32_e32 v58, 0xffff0000, v78
	s_waitcnt vmcnt(0)
	v_and_b32_e32 v57, 0xffff0000, v82
	v_lshlrev_b32_e32 v56, 16, v82
	v_mul_f32_e32 v57, v69, v57
	v_fmac_f32_e32 v57, v67, v56
	v_add_f32_e32 v56, 0, v57
	v_lshlrev_b32_e32 v57, 16, v78
	v_mul_f32_e32 v58, v71, v58
	v_fmac_f32_e32 v58, v68, v57
	v_add_f32_e32 v56, v58, v56
	v_and_b32_e32 v58, 0xffff0000, v83
	v_lshlrev_b32_e32 v57, 16, v83
	v_mul_f32_e32 v58, v73, v58
	v_fmac_f32_e32 v58, v70, v57
	v_add_f32_e32 v56, v58, v56
	v_and_b32_e32 v58, 0xffff0000, v79
	v_lshlrev_b32_e32 v57, 16, v79
	v_mul_f32_e32 v58, v74, v58
	v_fmac_f32_e32 v58, v72, v57
	v_add_f32_e32 v75, v58, v56
	v_and_b32_e32 v58, 0xffff0000, v76
	v_and_b32_e32 v79, 0xffff0000, v84
	v_and_b32_e32 v78, 0xffff0000, v80
	v_lshlrev_b32_e32 v57, 16, v62
	v_lshlrev_b32_e32 v56, 16, v76
	v_lshlrev_b32_e32 v61, 16, v84
	v_lshlrev_b32_e32 v60, 16, v80
	v_pk_mul_f32 v[78:79], v[58:59], v[78:79]
	v_and_b32_e32 v62, 0xffff0000, v77
	v_pk_fma_f32 v[60:61], v[56:57], v[60:61], v[78:79]
	v_and_b32_e32 v79, 0xffff0000, v85
	v_add_f32_e32 v61, v61, v75
	v_add_f32_e32 v75, v60, v61
	v_lshlrev_b32_e32 v61, 16, v63
	v_and_b32_e32 v63, 0xffff0000, v63
	v_and_b32_e32 v78, 0xffff0000, v81
	v_lshlrev_b32_e32 v60, 16, v77
	v_lshlrev_b32_e32 v77, 16, v85
	v_lshlrev_b32_e32 v76, 16, v81
	v_pk_mul_f32 v[78:79], v[62:63], v[78:79]
	s_nop 0
	v_pk_fma_f32 v[76:77], v[60:61], v[76:77], v[78:79]
	s_nop 0
	v_add_f32_e32 v75, v77, v75
	v_add_f32_e32 v75, v76, v75
	ds_bpermute_b32 v76, v161, v75
	s_waitcnt lgkmcnt(0)
	v_add_f32_e32 v75, v75, v76
	ds_bpermute_b32 v76, v163, v75
	s_waitcnt lgkmcnt(0)
	v_add_f32_e32 v75, v75, v76
	ds_bpermute_b32 v76, v165, v75
	s_waitcnt lgkmcnt(0)
	v_add_f32_e32 v75, v75, v76
	ds_bpermute_b32 v76, v167, v75
	s_waitcnt lgkmcnt(0)
	v_add_f32_e32 v75, v75, v76
	ds_bpermute_b32 v76, v169, v75
	s_waitcnt lgkmcnt(0)
	v_add_f32_e32 v75, v75, v76
	ds_bpermute_b32 v76, v184, v75
	s_waitcnt lgkmcnt(0)
	v_add_f32_e32 v75, v75, v76
	global_load_dwordx4 v[76:79], v88, s[6:7] offset:16
	global_load_dwordx4 v[80:83], v88, s[6:7] offset:48
	global_load_dwordx4 v[84:87], v88, s[6:7]
	s_nop 0
	global_load_dwordx4 v[88:91], v88, s[6:7] offset:32
	s_mov_b32 s6, 0x41700000
	s_waitcnt vmcnt(1)
	v_mov_b32_e32 v92, v84
	s_waitcnt vmcnt(0)
	v_mov_b32_e32 v93, v88
	v_mov_b32_e32 v88, v85
	v_pk_add_f32 v[84:85], v[92:93], v[88:89]
	v_mov_b32_e32 v88, v86
	v_mov_b32_e32 v89, v90
	v_mov_b32_e32 v90, v87
	v_pk_add_f32 v[86:87], v[88:89], v[90:91]
	s_nop 0
	v_pk_add_f32 v[84:85], v[84:85], v[86:87]
	v_mov_b32_e32 v86, v76
	v_mov_b32_e32 v87, v80
	v_mov_b32_e32 v80, v77
	v_pk_add_f32 v[76:77], v[86:87], v[80:81]
	v_mov_b32_e32 v80, v78
	v_mov_b32_e32 v81, v82
	v_mov_b32_e32 v82, v79
	v_pk_add_f32 v[78:79], v[80:81], v[82:83]
	s_nop 0
	v_pk_add_f32 v[76:77], v[76:77], v[78:79]
	s_nop 0
	v_pk_add_f32 v[76:77], v[84:85], v[76:77]
	s_nop 0
	v_add_f32_e32 v76, v76, v77
	v_fmamk_f32 v76, v76, 0x3a800000, v191
	v_cmp_gt_f32_e32 vcc, s71, v76
	v_mul_f32_e32 v77, 0x4b800000, v76
	s_nop 0
	v_cndmask_b32_e32 v76, v76, v77, vcc
	v_rsq_f32_e32 v76, v76
	s_nop 0
	v_mul_f32_e32 v77, 0x45800000, v76
	v_cndmask_b32_e32 v76, v76, v77, vcc
	global_load_dword v77, v3, s[2:3]
	s_waitcnt vmcnt(0)
	v_mov_b32_e32 v120, v77
	v_fmac_f32_e32 v77, v75, v76
	v_cmp_nlt_f32_e32 vcc, s6, v77
	s_and_saveexec_b64 s[6:7], vcc
	s_cbranch_execz .LBB0_723
	v_mul_f32_e32 v75, 0x3fb8aa3b, v77
	v_exp_f32_e32 v75, v75
	s_mov_b32 s8, 0x3f2aaaab
	v_add_f32_e32 v78, 1.0, v75
	v_frexp_mant_f32_e32 v80, v78
	v_cvt_f64_f32_e32 v[76:77], v78
	v_frexp_exp_i32_f64_e32 v76, v[76:77]
	v_cmp_gt_f32_e32 vcc, s8, v80
	v_add_f32_e32 v79, -1.0, v78
	v_sub_f32_e32 v81, v79, v78
	v_subbrev_co_u32_e32 v84, vcc, 0, v76, vcc
	v_sub_u32_e32 v76, 0, v84
	v_sub_f32_e32 v79, v75, v79
	v_add_f32_e32 v81, 1.0, v81
	v_ldexp_f32 v77, v78, v76
	v_add_f32_e32 v79, v79, v81
	v_add_f32_e32 v78, -1.0, v77
	v_add_f32_e32 v80, 1.0, v77
	v_ldexp_f32 v76, v79, v76
	v_add_f32_e32 v79, 1.0, v78
	v_add_f32_e32 v81, -1.0, v80
	v_sub_f32_e32 v79, v77, v79
	v_sub_f32_e32 v77, v77, v81
	v_add_f32_e32 v79, v76, v79
	v_add_f32_e32 v76, v76, v77
	v_add_f32_e32 v85, v80, v76
	v_rcp_f32_e32 v87, v85
	v_sub_f32_e32 v77, v85, v80
	v_sub_f32_e32 v86, v76, v77
	v_add_f32_e32 v77, v78, v79
	v_mul_f32_e32 v89, v77, v87
	v_sub_f32_e32 v76, v77, v78
	v_mul_f32_e32 v78, v85, v89
	v_fma_f32 v80, v89, v85, -v78
	v_fmac_f32_e32 v80, v89, v86
	v_sub_f32_e32 v88, v79, v76
	v_add_f32_e32 v76, v78, v80
	v_sub_f32_e32 v79, v77, v76
	v_pk_add_f32 v[82:83], v[76:77], v[78:79] neg_lo:[0,1] neg_hi:[0,1]
	v_mov_b32_e32 v81, v76
	v_pk_add_f32 v[76:77], v[82:83], v[80:81] neg_lo:[0,1] neg_hi:[0,1]
	s_mov_b32 s8, 0x3f317218
	v_add_f32_e32 v77, v88, v77
	v_add_f32_e32 v76, v76, v77
	v_add_f32_e32 v77, v79, v76
	v_mul_f32_e32 v88, v87, v77
	v_mul_f32_e32 v78, v85, v88
	v_fma_f32 v80, v88, v85, -v78
	v_fmac_f32_e32 v80, v88, v86
	v_sub_f32_e32 v79, v79, v77
	v_add_f32_e32 v85, v76, v79
	v_add_f32_e32 v76, v78, v80
	v_sub_f32_e32 v79, v77, v76
	v_pk_add_f32 v[82:83], v[76:77], v[78:79] neg_lo:[0,1] neg_hi:[0,1]
	v_mov_b32_e32 v81, v76
	v_pk_add_f32 v[76:77], v[82:83], v[80:81] neg_lo:[0,1] neg_hi:[0,1]
	s_nop 0
	v_add_f32_e32 v77, v85, v77
	v_add_f32_e32 v76, v76, v77
	v_add_f32_e32 v77, v89, v88
	v_add_f32_e32 v76, v79, v76
	v_sub_f32_e32 v78, v77, v89
	v_mul_f32_e32 v76, v87, v76
	v_sub_f32_e32 v78, v88, v78
	v_add_f32_e32 v78, v78, v76
	v_add_f32_e32 v80, v77, v78
	v_mul_f32_e32 v81, v80, v80
	v_fmamk_f32 v76, v81, 0x3e9b6dac, v195
	v_fmaak_f32 v137, v81, v76, 0x3f2aaada
	v_cvt_f32_i32_e32 v76, v84
	v_sub_f32_e32 v77, v80, v77
	v_sub_f32_e32 v77, v78, v77
	v_ldexp_f32 v82, v77, 1
	v_mul_f32_e32 v77, v80, v81
	v_ldexp_f32 v79, v80, 1
	v_pk_mul_f32 v[80:81], v[76:77], v[136:137]
	s_nop 0
	v_fma_f32 v78, v76, s8, -v80
	v_fmac_f32_e32 v78, 0xb102e308, v76
	v_pk_add_f32 v[76:77], v[80:81], v[78:79]
	s_mov_b32 s8, 0x7f800000
	v_sub_f32_e32 v79, v77, v79
	v_sub_f32_e32 v79, v81, v79
	v_add_f32_e32 v83, v82, v79
	v_mov_b32_e32 v82, v80
	v_pk_add_f32 v[80:81], v[76:77], v[80:81] neg_lo:[0,1] neg_hi:[0,1]
	v_pk_add_f32 v[84:85], v[76:77], v[82:83]
	v_mov_b32_e32 v79, v76
	v_mov_b32_e32 v81, v85
	v_pk_add_f32 v[86:87], v[78:79], v[80:81] neg_lo:[0,1] neg_hi:[0,1]
	v_pk_add_f32 v[78:79], v[78:79], v[80:81]
	v_mov_b32_e32 v82, v83
	v_pk_add_f32 v[80:81], v[78:79], v[76:77] op_sel:[1,0] op_sel_hi:[0,1] neg_lo:[0,1] neg_hi:[0,1]
	v_pk_add_f32 v[88:89], v[84:85], v[80:81] op_sel_hi:[1,0] neg_lo:[0,1] neg_hi:[0,1]
	v_mov_b32_e32 v84, v85
	v_mov_b32_e32 v85, v79
	v_pk_mov_b32 v[80:81], v[76:77], v[80:81] op_sel:[1,0]
	v_mov_b32_e32 v83, v76
	v_pk_add_f32 v[80:81], v[84:85], v[80:81] neg_lo:[0,1] neg_hi:[0,1]
	v_mov_b32_e32 v88, v86
	v_pk_add_f32 v[76:77], v[82:83], v[80:81] neg_lo:[0,1] neg_hi:[0,1]
	v_mov_b32_e32 v87, v79
	v_pk_add_f32 v[80:81], v[88:89], v[76:77]
	v_cmp_neq_f32_e32 vcc, s8, v75
	v_pk_add_f32 v[82:83], v[80:81], v[80:81] op_sel:[0,1] op_sel_hi:[1,0]
	s_mov_b32 s8, 0x33800000
	v_pk_add_f32 v[78:79], v[78:79], v[82:83] op_sel:[1,0] op_sel_hi:[0,1]
	v_mov_b32_e32 v81, v78
	v_pk_add_f32 v[84:85], v[80:81], v[86:87] neg_lo:[0,1] neg_hi:[0,1]
	v_mov_b32_e32 v77, v82
	v_sub_f32_e32 v79, v80, v84
	v_pk_add_f32 v[76:77], v[76:77], v[84:85] neg_lo:[0,1] neg_hi:[0,1]
	v_sub_f32_e32 v79, v86, v79
	v_add_f32_e32 v76, v76, v79
	v_add_f32_e32 v76, v76, v77
	v_add_f32_e32 v76, v78, v76
	v_cndmask_b32_e32 v76, v203, v76, vcc
	v_cmp_ngt_f32_e32 vcc, -1.0, v75
	s_nop 1
	v_cndmask_b32_e32 v76, v205, v76, vcc
	v_cmp_neq_f32_e32 vcc, -1.0, v75
	s_nop 1
	v_cndmask_b32_e32 v76, v204, v76, vcc
	v_cmp_lt_f32_e64 vcc, |v75|, s8
	s_nop 1
	v_cndmask_b32_e32 v77, v76, v75, vcc
.LBB0_723:
	s_or_b64 exec, exec, s[6:7]
	s_lshl_b32 s6, s95, 2
	v_cmp_eq_u32_e32 vcc, 0, v159
	s_add_i32 s16, s6, 0
	s_and_saveexec_b64 s[6:7], vcc
	v_mov_b32_e32 v75, s16
	ds_write_b32 v75, v77 offset:12288
	s_or_b64 exec, exec, s[6:7]
	s_or_b32 s6, s66, 0x8001
	s_lshl_b32 s8, s6, 11
	v_lshl_add_u64 v[80:81], v[54:55], 0, s[8:9]
	global_load_dwordx4 v[76:79], v[80:81], off offset:16
	s_nop 0
	global_load_dwordx4 v[80:83], v[80:81], off
	s_lshl_b32 s6, s6, 6
	v_mov_b32_e32 v88, s6
	v_readlane_b32 s6, v255, 11
	v_readlane_b32 s7, v255, 12
	s_waitcnt vmcnt(0)
	v_lshlrev_b32_e32 v75, 16, v80
	v_and_b32_e32 v80, 0xffff0000, v80
	v_mul_f32_e32 v80, v69, v80
	v_fmac_f32_e32 v80, v67, v75
	v_add_f32_e32 v75, 0, v80
	v_lshlrev_b32_e32 v80, 16, v76
	v_and_b32_e32 v76, 0xffff0000, v76
	v_mul_f32_e32 v76, v71, v76
	v_fmac_f32_e32 v76, v68, v80
	v_and_b32_e32 v80, 0xffff0000, v81
	v_add_f32_e32 v75, v76, v75
	v_lshlrev_b32_e32 v76, 16, v81
	v_mul_f32_e32 v80, v73, v80
	v_fmac_f32_e32 v80, v70, v76
	v_lshlrev_b32_e32 v76, 16, v77
	v_and_b32_e32 v77, 0xffff0000, v77
	v_mul_f32_e32 v77, v74, v77
	v_add_f32_e32 v75, v80, v75
	v_fmac_f32_e32 v77, v72, v76
	v_and_b32_e32 v81, 0xffff0000, v82
	v_and_b32_e32 v80, 0xffff0000, v78
	v_add_f32_e32 v75, v77, v75
	v_lshlrev_b32_e32 v77, 16, v82
	v_lshlrev_b32_e32 v76, 16, v78
	v_pk_mul_f32 v[80:81], v[58:59], v[80:81]
	s_nop 0
	v_pk_fma_f32 v[76:77], v[56:57], v[76:77], v[80:81]
	v_and_b32_e32 v81, 0xffff0000, v83
	v_add_f32_e32 v75, v77, v75
	v_and_b32_e32 v80, 0xffff0000, v79
	v_add_f32_e32 v75, v76, v75
	v_lshlrev_b32_e32 v77, 16, v83
	v_lshlrev_b32_e32 v76, 16, v79
	v_pk_mul_f32 v[78:79], v[62:63], v[80:81]
	s_nop 0
	v_pk_fma_f32 v[76:77], v[60:61], v[76:77], v[78:79]
	s_nop 0
	v_add_f32_e32 v75, v77, v75
	v_add_f32_e32 v75, v76, v75
	ds_bpermute_b32 v76, v161, v75
	s_waitcnt lgkmcnt(0)
	v_add_f32_e32 v75, v75, v76
	ds_bpermute_b32 v76, v163, v75
	s_waitcnt lgkmcnt(0)
	v_add_f32_e32 v75, v75, v76
	ds_bpermute_b32 v76, v165, v75
	s_waitcnt lgkmcnt(0)
	v_add_f32_e32 v75, v75, v76
	ds_bpermute_b32 v76, v167, v75
	s_waitcnt lgkmcnt(0)
	v_add_f32_e32 v75, v75, v76
	ds_bpermute_b32 v76, v169, v75
	s_waitcnt lgkmcnt(0)
	v_add_f32_e32 v75, v75, v76
	ds_bpermute_b32 v76, v184, v75
	s_waitcnt lgkmcnt(0)
	v_add_f32_e32 v75, v75, v76
	global_load_dwordx4 v[76:79], v88, s[6:7] offset:16
	global_load_dwordx4 v[80:83], v88, s[6:7] offset:48
	global_load_dwordx4 v[84:87], v88, s[6:7]
	s_nop 0
	global_load_dwordx4 v[88:91], v88, s[6:7] offset:32
	s_mov_b32 s6, 0x41700000
	s_waitcnt vmcnt(1)
	v_mov_b32_e32 v92, v84
	s_waitcnt vmcnt(0)
	v_mov_b32_e32 v93, v88
	v_mov_b32_e32 v88, v85
	v_pk_add_f32 v[84:85], v[92:93], v[88:89]
	v_mov_b32_e32 v88, v86
	v_mov_b32_e32 v89, v90
	v_mov_b32_e32 v90, v87
	v_pk_add_f32 v[86:87], v[88:89], v[90:91]
	s_nop 0
	v_pk_add_f32 v[84:85], v[84:85], v[86:87]
	v_mov_b32_e32 v86, v76
	v_mov_b32_e32 v87, v80
	v_mov_b32_e32 v80, v77
	v_pk_add_f32 v[76:77], v[86:87], v[80:81]
	v_mov_b32_e32 v80, v78
	v_mov_b32_e32 v81, v82
	v_mov_b32_e32 v82, v79
	v_pk_add_f32 v[78:79], v[80:81], v[82:83]
	s_nop 0
	v_pk_add_f32 v[76:77], v[76:77], v[78:79]
	s_nop 0
	v_pk_add_f32 v[76:77], v[84:85], v[76:77]
	s_nop 0
	v_add_f32_e32 v76, v76, v77
	v_fmamk_f32 v76, v76, 0x3a800000, v191
	v_cmp_gt_f32_e64 s[38:39], s71, v76
	v_mul_f32_e32 v77, 0x4b800000, v76
	s_nop 0
	v_cndmask_b32_e64 v76, v76, v77, s[38:39]
	v_rsq_f32_e32 v76, v76
	s_nop 0
	v_mul_f32_e32 v77, 0x45800000, v76
	v_cndmask_b32_e64 v77, v76, v77, s[38:39]
	v_mov_b32_e32 v76, v120
	s_waitcnt vmcnt(0)
	v_fmac_f32_e32 v76, v75, v77
	v_cmp_nlt_f32_e64 s[38:39], s6, v76
	s_and_saveexec_b64 s[6:7], s[38:39]
	s_cbranch_execz .LBB0_727
	v_mul_f32_e32 v75, 0x3fb8aa3b, v76
	v_exp_f32_e32 v75, v75
	s_mov_b32 s8, 0x3f2aaaab
	v_add_f32_e32 v78, 1.0, v75
	v_frexp_mant_f32_e32 v80, v78
	v_cvt_f64_f32_e32 v[76:77], v78
	v_frexp_exp_i32_f64_e32 v76, v[76:77]
	v_cmp_gt_f32_e64 s[38:39], s8, v80
	v_add_f32_e32 v79, -1.0, v78
	v_sub_f32_e32 v81, v79, v78
	v_subbrev_co_u32_e64 v84, s[38:39], 0, v76, s[38:39]
	v_sub_u32_e32 v76, 0, v84
	v_sub_f32_e32 v79, v75, v79
	v_add_f32_e32 v81, 1.0, v81
	v_ldexp_f32 v77, v78, v76
	v_add_f32_e32 v79, v79, v81
	v_add_f32_e32 v78, -1.0, v77
	v_add_f32_e32 v80, 1.0, v77
	v_ldexp_f32 v76, v79, v76
	v_add_f32_e32 v79, 1.0, v78
	v_add_f32_e32 v81, -1.0, v80
	v_sub_f32_e32 v79, v77, v79
	v_sub_f32_e32 v77, v77, v81
	v_add_f32_e32 v79, v76, v79
	v_add_f32_e32 v76, v76, v77
	v_add_f32_e32 v85, v80, v76
	v_rcp_f32_e32 v87, v85
	v_sub_f32_e32 v77, v85, v80
	v_sub_f32_e32 v86, v76, v77
	v_add_f32_e32 v77, v78, v79
	v_mul_f32_e32 v89, v77, v87
	v_sub_f32_e32 v76, v77, v78
	v_mul_f32_e32 v78, v85, v89
	v_fma_f32 v80, v89, v85, -v78
	v_fmac_f32_e32 v80, v89, v86
	v_sub_f32_e32 v88, v79, v76
	v_add_f32_e32 v76, v78, v80
	v_sub_f32_e32 v79, v77, v76
	v_pk_add_f32 v[82:83], v[76:77], v[78:79] neg_lo:[0,1] neg_hi:[0,1]
	v_mov_b32_e32 v81, v76
	v_pk_add_f32 v[76:77], v[82:83], v[80:81] neg_lo:[0,1] neg_hi:[0,1]
	s_mov_b32 s8, 0x3f317218
	v_add_f32_e32 v77, v88, v77
	v_add_f32_e32 v76, v76, v77
	v_add_f32_e32 v77, v79, v76
	v_mul_f32_e32 v88, v87, v77
	v_mul_f32_e32 v78, v85, v88
	v_fma_f32 v80, v88, v85, -v78
	v_fmac_f32_e32 v80, v88, v86
	v_sub_f32_e32 v79, v79, v77
	v_add_f32_e32 v85, v76, v79
	v_add_f32_e32 v76, v78, v80
	v_sub_f32_e32 v79, v77, v76
	v_pk_add_f32 v[82:83], v[76:77], v[78:79] neg_lo:[0,1] neg_hi:[0,1]
	v_mov_b32_e32 v81, v76
	v_pk_add_f32 v[76:77], v[82:83], v[80:81] neg_lo:[0,1] neg_hi:[0,1]
	s_nop 0
	v_add_f32_e32 v77, v85, v77
	v_add_f32_e32 v76, v76, v77
	v_add_f32_e32 v77, v89, v88
	v_add_f32_e32 v76, v79, v76
	v_sub_f32_e32 v78, v77, v89
	v_mul_f32_e32 v76, v87, v76
	v_sub_f32_e32 v78, v88, v78
	v_add_f32_e32 v78, v78, v76
	v_add_f32_e32 v80, v77, v78
	v_mul_f32_e32 v81, v80, v80
	v_fmamk_f32 v76, v81, 0x3e9b6dac, v195
	v_fmaak_f32 v137, v81, v76, 0x3f2aaada
	v_cvt_f32_i32_e32 v76, v84
	v_sub_f32_e32 v77, v80, v77
	v_sub_f32_e32 v77, v78, v77
	v_ldexp_f32 v82, v77, 1
	v_mul_f32_e32 v77, v80, v81
	v_ldexp_f32 v79, v80, 1
	v_pk_mul_f32 v[80:81], v[76:77], v[136:137]
	s_nop 0
	v_fma_f32 v78, v76, s8, -v80
	v_fmac_f32_e32 v78, 0xb102e308, v76
	v_pk_add_f32 v[76:77], v[80:81], v[78:79]
	s_mov_b32 s8, 0x7f800000
	v_sub_f32_e32 v79, v77, v79
	v_sub_f32_e32 v79, v81, v79
	v_add_f32_e32 v83, v82, v79
	v_mov_b32_e32 v82, v80
	v_pk_add_f32 v[80:81], v[76:77], v[80:81] neg_lo:[0,1] neg_hi:[0,1]
	v_pk_add_f32 v[84:85], v[76:77], v[82:83]
	v_mov_b32_e32 v79, v76
	v_mov_b32_e32 v81, v85
	v_pk_add_f32 v[86:87], v[78:79], v[80:81] neg_lo:[0,1] neg_hi:[0,1]
	v_pk_add_f32 v[78:79], v[78:79], v[80:81]
	v_mov_b32_e32 v82, v83
	v_pk_add_f32 v[80:81], v[78:79], v[76:77] op_sel:[1,0] op_sel_hi:[0,1] neg_lo:[0,1] neg_hi:[0,1]
	v_pk_add_f32 v[88:89], v[84:85], v[80:81] op_sel_hi:[1,0] neg_lo:[0,1] neg_hi:[0,1]
	v_mov_b32_e32 v84, v85
	v_mov_b32_e32 v85, v79
	v_pk_mov_b32 v[80:81], v[76:77], v[80:81] op_sel:[1,0]
	v_mov_b32_e32 v83, v76
	v_pk_add_f32 v[80:81], v[84:85], v[80:81] neg_lo:[0,1] neg_hi:[0,1]
	v_mov_b32_e32 v88, v86
	v_pk_add_f32 v[76:77], v[82:83], v[80:81] neg_lo:[0,1] neg_hi:[0,1]
	v_mov_b32_e32 v87, v79
	v_pk_add_f32 v[80:81], v[88:89], v[76:77]
	v_cmp_neq_f32_e64 s[38:39], s8, v75
	v_pk_add_f32 v[82:83], v[80:81], v[80:81] op_sel:[0,1] op_sel_hi:[1,0]
	s_mov_b32 s8, 0x33800000
	v_pk_add_f32 v[78:79], v[78:79], v[82:83] op_sel:[1,0] op_sel_hi:[0,1]
	v_mov_b32_e32 v81, v78
	v_pk_add_f32 v[84:85], v[80:81], v[86:87] neg_lo:[0,1] neg_hi:[0,1]
	v_mov_b32_e32 v77, v82
	v_sub_f32_e32 v79, v80, v84
	v_pk_add_f32 v[76:77], v[76:77], v[84:85] neg_lo:[0,1] neg_hi:[0,1]
	v_sub_f32_e32 v79, v86, v79
	v_add_f32_e32 v76, v76, v79
	v_add_f32_e32 v76, v76, v77
	v_add_f32_e32 v76, v78, v76
	v_cndmask_b32_e64 v76, v203, v76, s[38:39]
	v_cmp_ngt_f32_e64 s[38:39], -1.0, v75
	s_nop 1
	v_cndmask_b32_e64 v76, v205, v76, s[38:39]
	v_cmp_neq_f32_e64 s[38:39], -1.0, v75
	s_nop 1
	v_cndmask_b32_e64 v76, v204, v76, s[38:39]
	v_cmp_lt_f32_e64 s[38:39], |v75|, s8
	s_nop 1
	v_cndmask_b32_e64 v76, v76, v75, s[38:39]
.LBB0_727:
	s_or_b64 exec, exec, s[6:7]
	s_and_saveexec_b64 s[6:7], vcc
	v_mov_b32_e32 v75, s16
	ds_write_b32 v75, v76 offset:12320
	s_or_b64 exec, exec, s[6:7]
	s_or_b32 s6, s66, 0x8002
	s_lshl_b32 s8, s6, 11
	v_lshl_add_u64 v[80:81], v[54:55], 0, s[8:9]
	global_load_dwordx4 v[76:79], v[80:81], off offset:16
	s_nop 0
	global_load_dwordx4 v[80:83], v[80:81], off
	s_lshl_b32 s6, s6, 6
	v_mov_b32_e32 v88, s6
	v_readlane_b32 s6, v255, 11
	v_readlane_b32 s7, v255, 12
	s_waitcnt vmcnt(0)
	v_lshlrev_b32_e32 v75, 16, v80
	v_and_b32_e32 v80, 0xffff0000, v80
	v_mul_f32_e32 v80, v69, v80
	v_fmac_f32_e32 v80, v67, v75
	v_add_f32_e32 v75, 0, v80
	v_lshlrev_b32_e32 v80, 16, v76
	v_and_b32_e32 v76, 0xffff0000, v76
	v_mul_f32_e32 v76, v71, v76
	v_fmac_f32_e32 v76, v68, v80
	v_and_b32_e32 v80, 0xffff0000, v81
	v_add_f32_e32 v75, v76, v75
	v_lshlrev_b32_e32 v76, 16, v81
	v_mul_f32_e32 v80, v73, v80
	v_fmac_f32_e32 v80, v70, v76
	v_lshlrev_b32_e32 v76, 16, v77
	v_and_b32_e32 v77, 0xffff0000, v77
	v_mul_f32_e32 v77, v74, v77
	v_add_f32_e32 v75, v80, v75
	v_fmac_f32_e32 v77, v72, v76
	v_and_b32_e32 v81, 0xffff0000, v82
	v_and_b32_e32 v80, 0xffff0000, v78
	v_add_f32_e32 v75, v77, v75
	v_lshlrev_b32_e32 v77, 16, v82
	v_lshlrev_b32_e32 v76, 16, v78
	v_pk_mul_f32 v[80:81], v[58:59], v[80:81]
	s_nop 0
	v_pk_fma_f32 v[76:77], v[56:57], v[76:77], v[80:81]
	v_and_b32_e32 v81, 0xffff0000, v83
	v_add_f32_e32 v75, v77, v75
	v_and_b32_e32 v80, 0xffff0000, v79
	v_add_f32_e32 v75, v76, v75
	v_lshlrev_b32_e32 v77, 16, v83
	v_lshlrev_b32_e32 v76, 16, v79
	v_pk_mul_f32 v[78:79], v[62:63], v[80:81]
	s_nop 0
	v_pk_fma_f32 v[76:77], v[60:61], v[76:77], v[78:79]
	s_nop 0
	v_add_f32_e32 v75, v77, v75
	v_add_f32_e32 v75, v76, v75
	ds_bpermute_b32 v76, v161, v75
	s_waitcnt lgkmcnt(0)
	v_add_f32_e32 v75, v75, v76
	ds_bpermute_b32 v76, v163, v75
	s_waitcnt lgkmcnt(0)
	v_add_f32_e32 v75, v75, v76
	ds_bpermute_b32 v76, v165, v75
	s_waitcnt lgkmcnt(0)
	v_add_f32_e32 v75, v75, v76
	ds_bpermute_b32 v76, v167, v75
	s_waitcnt lgkmcnt(0)
	v_add_f32_e32 v75, v75, v76
	ds_bpermute_b32 v76, v169, v75
	s_waitcnt lgkmcnt(0)
	v_add_f32_e32 v75, v75, v76
	ds_bpermute_b32 v76, v184, v75
	s_waitcnt lgkmcnt(0)
	v_add_f32_e32 v75, v75, v76
	global_load_dwordx4 v[76:79], v88, s[6:7] offset:16
	global_load_dwordx4 v[80:83], v88, s[6:7] offset:48
	global_load_dwordx4 v[84:87], v88, s[6:7]
	s_nop 0
	global_load_dwordx4 v[88:91], v88, s[6:7] offset:32
	s_mov_b32 s6, 0x41700000
	s_waitcnt vmcnt(1)
	v_mov_b32_e32 v92, v84
	s_waitcnt vmcnt(0)
	v_mov_b32_e32 v93, v88
	v_mov_b32_e32 v88, v85
	v_pk_add_f32 v[84:85], v[92:93], v[88:89]
	v_mov_b32_e32 v88, v86
	v_mov_b32_e32 v89, v90
	v_mov_b32_e32 v90, v87
	v_pk_add_f32 v[86:87], v[88:89], v[90:91]
	s_nop 0
	v_pk_add_f32 v[84:85], v[84:85], v[86:87]
	v_mov_b32_e32 v86, v76
	v_mov_b32_e32 v87, v80
	v_mov_b32_e32 v80, v77
	v_pk_add_f32 v[76:77], v[86:87], v[80:81]
	v_mov_b32_e32 v80, v78
	v_mov_b32_e32 v81, v82
	v_mov_b32_e32 v82, v79
	v_pk_add_f32 v[78:79], v[80:81], v[82:83]
	s_nop 0
	v_pk_add_f32 v[76:77], v[76:77], v[78:79]
	s_nop 0
	v_pk_add_f32 v[76:77], v[84:85], v[76:77]
	s_nop 0
	v_add_f32_e32 v76, v76, v77
	v_fmamk_f32 v76, v76, 0x3a800000, v191
	v_cmp_gt_f32_e64 s[38:39], s71, v76
	v_mul_f32_e32 v77, 0x4b800000, v76
	s_nop 0
	v_cndmask_b32_e64 v76, v76, v77, s[38:39]
	v_rsq_f32_e32 v76, v76
	s_nop 0
	v_mul_f32_e32 v77, 0x45800000, v76
	v_cndmask_b32_e64 v77, v76, v77, s[38:39]
	v_mov_b32_e32 v76, v120
	s_waitcnt vmcnt(0)
	v_fmac_f32_e32 v76, v75, v77
	v_cmp_nlt_f32_e64 s[38:39], s6, v76
	s_and_saveexec_b64 s[6:7], s[38:39]
	s_cbranch_execz .LBB0_731
	v_mul_f32_e32 v75, 0x3fb8aa3b, v76
	v_exp_f32_e32 v75, v75
	s_mov_b32 s8, 0x3f2aaaab
	v_add_f32_e32 v78, 1.0, v75
	v_frexp_mant_f32_e32 v80, v78
	v_cvt_f64_f32_e32 v[76:77], v78
	v_frexp_exp_i32_f64_e32 v76, v[76:77]
	v_cmp_gt_f32_e64 s[38:39], s8, v80
	v_add_f32_e32 v79, -1.0, v78
	v_sub_f32_e32 v81, v79, v78
	v_subbrev_co_u32_e64 v84, s[38:39], 0, v76, s[38:39]
	v_sub_u32_e32 v76, 0, v84
	v_sub_f32_e32 v79, v75, v79
	v_add_f32_e32 v81, 1.0, v81
	v_ldexp_f32 v77, v78, v76
	v_add_f32_e32 v79, v79, v81
	v_add_f32_e32 v78, -1.0, v77
	v_add_f32_e32 v80, 1.0, v77
	v_ldexp_f32 v76, v79, v76
	v_add_f32_e32 v79, 1.0, v78
	v_add_f32_e32 v81, -1.0, v80
	v_sub_f32_e32 v79, v77, v79
	v_sub_f32_e32 v77, v77, v81
	v_add_f32_e32 v79, v76, v79
	v_add_f32_e32 v76, v76, v77
	v_add_f32_e32 v85, v80, v76
	v_rcp_f32_e32 v87, v85
	v_sub_f32_e32 v77, v85, v80
	v_sub_f32_e32 v86, v76, v77
	v_add_f32_e32 v77, v78, v79
	v_mul_f32_e32 v89, v77, v87
	v_sub_f32_e32 v76, v77, v78
	v_mul_f32_e32 v78, v85, v89
	v_fma_f32 v80, v89, v85, -v78
	v_fmac_f32_e32 v80, v89, v86
	v_sub_f32_e32 v88, v79, v76
	v_add_f32_e32 v76, v78, v80
	v_sub_f32_e32 v79, v77, v76
	v_pk_add_f32 v[82:83], v[76:77], v[78:79] neg_lo:[0,1] neg_hi:[0,1]
	v_mov_b32_e32 v81, v76
	v_pk_add_f32 v[76:77], v[82:83], v[80:81] neg_lo:[0,1] neg_hi:[0,1]
	s_mov_b32 s8, 0x3f317218
	v_add_f32_e32 v77, v88, v77
	v_add_f32_e32 v76, v76, v77
	v_add_f32_e32 v77, v79, v76
	v_mul_f32_e32 v88, v87, v77
	v_mul_f32_e32 v78, v85, v88
	v_fma_f32 v80, v88, v85, -v78
	v_fmac_f32_e32 v80, v88, v86
	v_sub_f32_e32 v79, v79, v77
	v_add_f32_e32 v85, v76, v79
	v_add_f32_e32 v76, v78, v80
	v_sub_f32_e32 v79, v77, v76
	v_pk_add_f32 v[82:83], v[76:77], v[78:79] neg_lo:[0,1] neg_hi:[0,1]
	v_mov_b32_e32 v81, v76
	v_pk_add_f32 v[76:77], v[82:83], v[80:81] neg_lo:[0,1] neg_hi:[0,1]
	s_nop 0
	v_add_f32_e32 v77, v85, v77
	v_add_f32_e32 v76, v76, v77
	v_add_f32_e32 v77, v89, v88
	v_add_f32_e32 v76, v79, v76
	v_sub_f32_e32 v78, v77, v89
	v_mul_f32_e32 v76, v87, v76
	v_sub_f32_e32 v78, v88, v78
	v_add_f32_e32 v78, v78, v76
	v_add_f32_e32 v80, v77, v78
	v_mul_f32_e32 v81, v80, v80
	v_fmamk_f32 v76, v81, 0x3e9b6dac, v195
	v_fmaak_f32 v137, v81, v76, 0x3f2aaada
	v_cvt_f32_i32_e32 v76, v84
	v_sub_f32_e32 v77, v80, v77
	v_sub_f32_e32 v77, v78, v77
	v_ldexp_f32 v82, v77, 1
	v_mul_f32_e32 v77, v80, v81
	v_ldexp_f32 v79, v80, 1
	v_pk_mul_f32 v[80:81], v[76:77], v[136:137]
	s_nop 0
	v_fma_f32 v78, v76, s8, -v80
	v_fmac_f32_e32 v78, 0xb102e308, v76
	v_pk_add_f32 v[76:77], v[80:81], v[78:79]
	s_mov_b32 s8, 0x7f800000
	v_sub_f32_e32 v79, v77, v79
	v_sub_f32_e32 v79, v81, v79
	v_add_f32_e32 v83, v82, v79
	v_mov_b32_e32 v82, v80
	v_pk_add_f32 v[80:81], v[76:77], v[80:81] neg_lo:[0,1] neg_hi:[0,1]
	v_pk_add_f32 v[84:85], v[76:77], v[82:83]
	v_mov_b32_e32 v79, v76
	v_mov_b32_e32 v81, v85
	v_pk_add_f32 v[86:87], v[78:79], v[80:81] neg_lo:[0,1] neg_hi:[0,1]
	v_pk_add_f32 v[78:79], v[78:79], v[80:81]
	v_mov_b32_e32 v82, v83
	v_pk_add_f32 v[80:81], v[78:79], v[76:77] op_sel:[1,0] op_sel_hi:[0,1] neg_lo:[0,1] neg_hi:[0,1]
	v_pk_add_f32 v[88:89], v[84:85], v[80:81] op_sel_hi:[1,0] neg_lo:[0,1] neg_hi:[0,1]
	v_mov_b32_e32 v84, v85
	v_mov_b32_e32 v85, v79
	v_pk_mov_b32 v[80:81], v[76:77], v[80:81] op_sel:[1,0]
	v_mov_b32_e32 v83, v76
	v_pk_add_f32 v[80:81], v[84:85], v[80:81] neg_lo:[0,1] neg_hi:[0,1]
	v_mov_b32_e32 v88, v86
	v_pk_add_f32 v[76:77], v[82:83], v[80:81] neg_lo:[0,1] neg_hi:[0,1]
	v_mov_b32_e32 v87, v79
	v_pk_add_f32 v[80:81], v[88:89], v[76:77]
	v_cmp_neq_f32_e64 s[38:39], s8, v75
	v_pk_add_f32 v[82:83], v[80:81], v[80:81] op_sel:[0,1] op_sel_hi:[1,0]
	s_mov_b32 s8, 0x33800000
	v_pk_add_f32 v[78:79], v[78:79], v[82:83] op_sel:[1,0] op_sel_hi:[0,1]
	v_mov_b32_e32 v81, v78
	v_pk_add_f32 v[84:85], v[80:81], v[86:87] neg_lo:[0,1] neg_hi:[0,1]
	v_mov_b32_e32 v77, v82
	v_sub_f32_e32 v79, v80, v84
	v_pk_add_f32 v[76:77], v[76:77], v[84:85] neg_lo:[0,1] neg_hi:[0,1]
	v_sub_f32_e32 v79, v86, v79
	v_add_f32_e32 v76, v76, v79
	v_add_f32_e32 v76, v76, v77
	v_add_f32_e32 v76, v78, v76
	v_cndmask_b32_e64 v76, v203, v76, s[38:39]
	v_cmp_ngt_f32_e64 s[38:39], -1.0, v75
	s_nop 1
	v_cndmask_b32_e64 v76, v205, v76, s[38:39]
	v_cmp_neq_f32_e64 s[38:39], -1.0, v75
	s_nop 1
	v_cndmask_b32_e64 v76, v204, v76, s[38:39]
	v_cmp_lt_f32_e64 s[38:39], |v75|, s8
	s_nop 1
	v_cndmask_b32_e64 v76, v76, v75, s[38:39]
.LBB0_731:
	s_or_b64 exec, exec, s[6:7]
	s_and_saveexec_b64 s[6:7], vcc
	v_mov_b32_e32 v75, s16
	ds_write_b32 v75, v76 offset:12352
	s_or_b64 exec, exec, s[6:7]
	s_or_b32 s6, s66, 0x8003
	s_lshl_b32 s8, s6, 11
	v_lshl_add_u64 v[54:55], v[54:55], 0, s[8:9]
	global_load_dwordx4 v[76:79], v[54:55], off offset:16
	global_load_dwordx4 v[80:83], v[54:55], off
	s_lshl_b32 s6, s6, 6
	s_waitcnt vmcnt(0)
	v_and_b32_e32 v55, 0xffff0000, v80
	v_lshlrev_b32_e32 v54, 16, v80
	v_mul_f32_e32 v55, v69, v55
	v_fmac_f32_e32 v55, v67, v54
	v_and_b32_e32 v67, 0xffff0000, v76
	v_add_f32_e32 v54, 0, v55
	v_lshlrev_b32_e32 v55, 16, v76
	v_mul_f32_e32 v67, v71, v67
	v_fmac_f32_e32 v67, v68, v55
	v_add_f32_e32 v54, v67, v54
	v_and_b32_e32 v67, 0xffff0000, v81
	v_lshlrev_b32_e32 v55, 16, v81
	v_mul_f32_e32 v67, v73, v67
	v_fmac_f32_e32 v67, v70, v55
	v_add_f32_e32 v54, v67, v54
	v_and_b32_e32 v67, 0xffff0000, v77
	v_lshlrev_b32_e32 v55, 16, v77
	v_mul_f32_e32 v67, v74, v67
	v_fmac_f32_e32 v67, v72, v55
	v_and_b32_e32 v69, 0xffff0000, v82
	v_and_b32_e32 v68, 0xffff0000, v78
	v_add_f32_e32 v67, v67, v54
	v_lshlrev_b32_e32 v55, 16, v82
	v_lshlrev_b32_e32 v54, 16, v78
	v_pk_mul_f32 v[58:59], v[58:59], v[68:69]
	s_nop 0
	v_pk_fma_f32 v[54:55], v[56:57], v[54:55], v[58:59]
	v_and_b32_e32 v57, 0xffff0000, v83
	v_add_f32_e32 v55, v55, v67
	v_and_b32_e32 v56, 0xffff0000, v79
	v_add_f32_e32 v58, v54, v55
	v_lshlrev_b32_e32 v55, 16, v83
	v_lshlrev_b32_e32 v54, 16, v79
	v_pk_mul_f32 v[56:57], v[62:63], v[56:57]
	s_nop 0
	v_pk_fma_f32 v[54:55], v[60:61], v[54:55], v[56:57]
	s_nop 0
	v_add_f32_e32 v55, v55, v58
	v_add_f32_e32 v54, v54, v55
	ds_bpermute_b32 v55, v161, v54
	s_waitcnt lgkmcnt(0)
	v_add_f32_e32 v54, v54, v55
	ds_bpermute_b32 v55, v163, v54
	s_waitcnt lgkmcnt(0)
	v_add_f32_e32 v54, v54, v55
	ds_bpermute_b32 v55, v165, v54
	s_waitcnt lgkmcnt(0)
	v_add_f32_e32 v54, v54, v55
	ds_bpermute_b32 v55, v167, v54
	s_waitcnt lgkmcnt(0)
	v_add_f32_e32 v54, v54, v55
	ds_bpermute_b32 v55, v169, v54
	s_waitcnt lgkmcnt(0)
	v_add_f32_e32 v54, v54, v55
	ds_bpermute_b32 v55, v184, v54
	s_waitcnt lgkmcnt(0)
	v_add_f32_e32 v54, v54, v55
	v_mov_b32_e32 v55, s6
	v_readlane_b32 s6, v255, 11
	v_readlane_b32 s7, v255, 12
	s_nop 4
	global_load_dwordx4 v[56:59], v55, s[6:7] offset:16
	global_load_dwordx4 v[60:63], v55, s[6:7] offset:48
	global_load_dwordx4 v[68:71], v55, s[6:7]
	global_load_dwordx4 v[72:75], v55, s[6:7] offset:32
	s_waitcnt vmcnt(1)
	v_mov_b32_e32 v76, v68
	s_waitcnt vmcnt(0)
	v_mov_b32_e32 v77, v72
	v_mov_b32_e32 v72, v69
	v_pk_add_f32 v[68:69], v[76:77], v[72:73]
	v_mov_b32_e32 v72, v70
	v_mov_b32_e32 v73, v74
	v_mov_b32_e32 v74, v71
	v_pk_add_f32 v[70:71], v[72:73], v[74:75]
	s_nop 0
	v_pk_add_f32 v[68:69], v[68:69], v[70:71]
	v_mov_b32_e32 v70, v56
	v_mov_b32_e32 v71, v60
	v_mov_b32_e32 v60, v57
	v_pk_add_f32 v[56:57], v[70:71], v[60:61]
	v_mov_b32_e32 v60, v58
	v_mov_b32_e32 v61, v62
	v_mov_b32_e32 v62, v59
	v_pk_add_f32 v[58:59], v[60:61], v[62:63]
	s_nop 0
	v_pk_add_f32 v[56:57], v[56:57], v[58:59]
	s_nop 0
	v_pk_add_f32 v[56:57], v[68:69], v[56:57]
	s_nop 0
	v_add_f32_e32 v55, v56, v57
	v_fmamk_f32 v55, v55, 0x3a800000, v191
	v_cmp_gt_f32_e64 s[38:39], s71, v55
	v_mul_f32_e32 v56, 0x4b800000, v55
	s_nop 0
	v_cndmask_b32_e64 v55, v55, v56, s[38:39]
	v_rsq_f32_e32 v55, v55
	s_nop 0
	v_mul_f32_e32 v56, 0x45800000, v55
	v_cndmask_b32_e64 v56, v55, v56, s[38:39]
	v_mov_b32_e32 v55, v120
	s_mov_b32 s2, 0x41700000
	s_waitcnt vmcnt(0)
	v_fmac_f32_e32 v55, v54, v56
	v_cmp_nlt_f32_e64 s[38:39], s2, v55
	s_and_saveexec_b64 s[2:3], s[38:39]
	s_cbranch_execz .LBB0_735
	v_mul_f32_e32 v54, 0x3fb8aa3b, v55
	v_exp_f32_e32 v67, v54
	s_mov_b32 s6, 0x3f2aaaab
	v_add_f32_e32 v56, 1.0, v67
	v_frexp_mant_f32_e32 v58, v56
	v_cvt_f64_f32_e32 v[54:55], v56
	v_frexp_exp_i32_f64_e32 v54, v[54:55]
	v_cmp_gt_f32_e64 s[38:39], s6, v58
	v_add_f32_e32 v57, -1.0, v56
	v_sub_f32_e32 v59, v57, v56
	v_subbrev_co_u32_e64 v62, s[38:39], 0, v54, s[38:39]
	v_sub_u32_e32 v54, 0, v62
	v_sub_f32_e32 v57, v67, v57
	v_add_f32_e32 v59, 1.0, v59
	v_ldexp_f32 v55, v56, v54
	v_add_f32_e32 v57, v57, v59
	v_add_f32_e32 v56, -1.0, v55
	v_add_f32_e32 v58, 1.0, v55
	v_ldexp_f32 v54, v57, v54
	v_add_f32_e32 v57, 1.0, v56
	v_add_f32_e32 v59, -1.0, v58
	v_sub_f32_e32 v57, v55, v57
	v_sub_f32_e32 v55, v55, v59
	v_add_f32_e32 v57, v54, v57
	v_add_f32_e32 v54, v54, v55
	v_add_f32_e32 v63, v58, v54
	v_rcp_f32_e32 v69, v63
	v_sub_f32_e32 v55, v63, v58
	v_sub_f32_e32 v68, v54, v55
	v_add_f32_e32 v55, v56, v57
	v_mul_f32_e32 v71, v55, v69
	v_sub_f32_e32 v54, v55, v56
	v_mul_f32_e32 v56, v63, v71
	v_fma_f32 v58, v71, v63, -v56
	v_fmac_f32_e32 v58, v71, v68
	v_sub_f32_e32 v70, v57, v54
	v_add_f32_e32 v54, v56, v58
	v_sub_f32_e32 v57, v55, v54
	v_pk_add_f32 v[60:61], v[54:55], v[56:57] neg_lo:[0,1] neg_hi:[0,1]
	v_mov_b32_e32 v59, v54
	v_pk_add_f32 v[54:55], v[60:61], v[58:59] neg_lo:[0,1] neg_hi:[0,1]
	s_mov_b32 s6, 0x3f317218
	v_add_f32_e32 v55, v70, v55
	v_add_f32_e32 v54, v54, v55
	v_add_f32_e32 v55, v57, v54
	v_mul_f32_e32 v70, v69, v55
	v_mul_f32_e32 v56, v63, v70
	v_fma_f32 v58, v70, v63, -v56
	v_fmac_f32_e32 v58, v70, v68
	v_sub_f32_e32 v57, v57, v55
	v_add_f32_e32 v63, v54, v57
	v_add_f32_e32 v54, v56, v58
	v_sub_f32_e32 v57, v55, v54
	v_pk_add_f32 v[60:61], v[54:55], v[56:57] neg_lo:[0,1] neg_hi:[0,1]
	v_mov_b32_e32 v59, v54
	v_pk_add_f32 v[54:55], v[60:61], v[58:59] neg_lo:[0,1] neg_hi:[0,1]
	s_nop 0
	v_add_f32_e32 v55, v63, v55
	v_add_f32_e32 v54, v54, v55
	v_add_f32_e32 v55, v71, v70
	v_add_f32_e32 v54, v57, v54
	v_sub_f32_e32 v56, v55, v71
	v_mul_f32_e32 v54, v69, v54
	v_sub_f32_e32 v56, v70, v56
	v_add_f32_e32 v56, v56, v54
	v_add_f32_e32 v58, v55, v56
	v_mul_f32_e32 v59, v58, v58
	v_fmamk_f32 v54, v59, 0x3e9b6dac, v195
	v_fmaak_f32 v137, v59, v54, 0x3f2aaada
	v_cvt_f32_i32_e32 v54, v62
	v_sub_f32_e32 v55, v58, v55
	v_sub_f32_e32 v55, v56, v55
	v_ldexp_f32 v60, v55, 1
	v_mul_f32_e32 v55, v58, v59
	v_ldexp_f32 v57, v58, 1
	v_pk_mul_f32 v[58:59], v[54:55], v[136:137]
	s_nop 0
	v_fma_f32 v56, v54, s6, -v58
	v_fmac_f32_e32 v56, 0xb102e308, v54
	v_pk_add_f32 v[54:55], v[58:59], v[56:57]
	s_mov_b32 s6, 0x7f800000
	v_sub_f32_e32 v57, v55, v57
	v_sub_f32_e32 v57, v59, v57
	v_add_f32_e32 v61, v60, v57
	v_mov_b32_e32 v60, v58
	v_pk_add_f32 v[58:59], v[54:55], v[58:59] neg_lo:[0,1] neg_hi:[0,1]
	v_pk_add_f32 v[62:63], v[54:55], v[60:61]
	v_mov_b32_e32 v57, v54
	v_mov_b32_e32 v59, v63
	v_pk_add_f32 v[68:69], v[56:57], v[58:59] neg_lo:[0,1] neg_hi:[0,1]
	v_pk_add_f32 v[56:57], v[56:57], v[58:59]
	v_mov_b32_e32 v60, v61
	v_pk_add_f32 v[58:59], v[56:57], v[54:55] op_sel:[1,0] op_sel_hi:[0,1] neg_lo:[0,1] neg_hi:[0,1]
	v_pk_add_f32 v[70:71], v[62:63], v[58:59] op_sel_hi:[1,0] neg_lo:[0,1] neg_hi:[0,1]
	v_mov_b32_e32 v62, v63
	v_mov_b32_e32 v63, v57
	v_pk_mov_b32 v[58:59], v[54:55], v[58:59] op_sel:[1,0]
	v_mov_b32_e32 v61, v54
	v_pk_add_f32 v[58:59], v[62:63], v[58:59] neg_lo:[0,1] neg_hi:[0,1]
	v_mov_b32_e32 v70, v68
	v_pk_add_f32 v[54:55], v[60:61], v[58:59] neg_lo:[0,1] neg_hi:[0,1]
	v_mov_b32_e32 v69, v57
	v_pk_add_f32 v[58:59], v[70:71], v[54:55]
	v_cmp_neq_f32_e64 s[38:39], s6, v67
	v_pk_add_f32 v[60:61], v[58:59], v[58:59] op_sel:[0,1] op_sel_hi:[1,0]
	s_mov_b32 s6, 0x33800000
	v_pk_add_f32 v[56:57], v[56:57], v[60:61] op_sel:[1,0] op_sel_hi:[0,1]
	v_mov_b32_e32 v59, v56
	v_pk_add_f32 v[62:63], v[58:59], v[68:69] neg_lo:[0,1] neg_hi:[0,1]
	v_mov_b32_e32 v55, v60
	v_sub_f32_e32 v57, v58, v62
	v_pk_add_f32 v[54:55], v[54:55], v[62:63] neg_lo:[0,1] neg_hi:[0,1]
	v_sub_f32_e32 v57, v68, v57
	v_add_f32_e32 v54, v54, v57
	v_add_f32_e32 v54, v54, v55
	v_add_f32_e32 v54, v56, v54
	v_cndmask_b32_e64 v54, v203, v54, s[38:39]
	v_cmp_ngt_f32_e64 s[38:39], -1.0, v67
	s_nop 1
	v_cndmask_b32_e64 v54, v205, v54, s[38:39]
	v_cmp_neq_f32_e64 s[38:39], -1.0, v67
	s_nop 1
	v_cndmask_b32_e64 v54, v204, v54, s[38:39]
	v_cmp_lt_f32_e64 s[38:39], |v67|, s6
	s_nop 1
	v_cndmask_b32_e64 v55, v54, v67, s[38:39]
